# v106 + ph_post2: hand-written gated-merge epilogue (gate and Y1 loads pipelined 4 rows deep, packed f32 math, same op order)
# speedup vs baseline: 1.0085x; 1.0006x over previous
; DI float bflo(unsigned u) { return __uint_as_float(u << 16); }
;     DI void operator()(const f32x4 (&acc)[2][2][4][2], const Unit& u, int wr, int wc, int fr, int fq) const {
;         const int col0 = u.pn * BM + wc * 32 + 8 * fq;
;         const int rowb = u.pm * BM + wr * 64 + fr;
;         f32x4 bb[2][2];
; #pragma unroll
;         for (int bj = 0; bj < 2; ++bj) { bb[bj][0] = *(const f32x4*)(bg + col0 + bj * HALF); bb[bj][1] = *(const f32x4*)(bg + col0 + bj * HALF + 4); }
; #pragma unroll
;         for (int ai = 0; ai < 2; ++ai)
; #pragma unroll
;             for (int mp = 0; mp < 2; ++mp) {
;                 u32x4 zg[2][2], yv[2][2];
; #pragma unroll
;                 for (int mm = 0; mm < 2; ++mm)
; #pragma unroll
;                     for (int bj = 0; bj < 2; ++bj) { const int row = rowb + ai * HALF + (2 * mp + mm) * 16, col = col0 + bj * HALF;
;                         zg[mm][bj] = *(const u32x4*)(Zg + (size_t)row * INW + col);
;                         if (SECOND) yv[mm][bj] = *(const u32x4*)(Y1 + (size_t)row * D + col); }
;                 asm volatile("" ::: "memory");
; #pragma unroll
;                 for (int mm = 0; mm < 2; ++mm)
; #pragma unroll
;                     for (int bj = 0; bj < 2; ++bj) { const int m = 2 * mp + mm; const int row = rowb + ai * HALF + m * 16, col = col0 + bj * HALF;
;                         const u32x4 z = zg[mm][bj]; const f32x4 b0 = bb[bj][0], b1 = bb[bj][1];
;                         f32x4 g0, g1;
;                         g0[0] = fsigmoid(bflo(z.x) + b0[0]); g0[1] = fsigmoid(bfhi(z.x) + b0[1]); g0[2] = fsigmoid(bflo(z.y) + b0[2]); g0[3] = fsigmoid(bfhi(z.y) + b0[3]);
;                         g1[0] = fsigmoid(bflo(z.z) + b1[0]); g1[1] = fsigmoid(bfhi(z.z) + b1[1]); g1[2] = fsigmoid(bflo(z.w) + b1[2]); g1[3] = fsigmoid(bfhi(z.w) + b1[3]);
;                         f32x4 v0 = g0 * acc[ai][bj][m][0], v1 = g1 * acc[ai][bj][m][1];
;                         if (SECOND) { const u32x4 y = yv[mm][bj];
;                             v0[0] += bflo(y.x); v0[1] += bfhi(y.x); v0[2] += bflo(y.y); v0[3] += bfhi(y.y); v1[0] += bflo(y.z); v1[1] += bfhi(y.z); v1[2] += bflo(y.w); v1[3] += bfhi(y.w); }
;                         u32x4 w; w.x = pk2(v0[0], v0[1]); w.y = pk2(v0[2], v0[3]); w.z = pk2(v1[0], v1[1]); w.w = pk2(v1[2], v1[3]);
;                         *(u32x4*)((SECOND ? Mb : Y1) + (size_t)row * D + col) = w; }
.LBB0_542:
	v_lshl_or_b32 v241, s22, 8, v183
	v_lshl_add_u32 v240, s64, 8, v1
	v_lshlrev_b32_e32 v185, 2, v241
	v_mul_lo_u32 v182, v240, s78
	global_load_dwordx4 v[162:165], v185, s[48:49]
	global_load_dwordx4 v[166:169], v185, s[48:49] offset:16
	global_load_dwordx4 v[170:173], v185, s[48:49] offset:512
	global_load_dwordx4 v[218:221], v185, s[48:49] offset:528
	v_lshlrev_b32_e32 v184, 11, v240
	v_lshl_add_u32 v182, v241, 1, v182
	v_lshl_add_u32 v184, v241, 1, v184
	v_mov_b32_e32 v174, v182
	global_load_dwordx4 v[174:177], v174, s[8:9]
	v_mov_b32_e32 v178, v182
	global_load_dwordx4 v[178:181], v178, s[8:9] offset:256
	v_mov_b32_e32 v66, v184
	global_load_dwordx4 v[66:69], v66, s[50:51]
	v_mov_b32_e32 v70, v184
	global_load_dwordx4 v[70:73], v70, s[50:51] offset:256
	v_add_u32_e32 v186, 0x4c000, v182
	global_load_dwordx4 v[186:189], v186, s[8:9]
	v_add_u32_e32 v190, 0x4c000, v182
	global_load_dwordx4 v[190:193], v190, s[8:9] offset:256
	v_add_u32_e32 v82, 0x8000, v184
	global_load_dwordx4 v[82:85], v82, s[50:51]
	v_add_u32_e32 v86, 0x8000, v184
	global_load_dwordx4 v[86:89], v86, s[50:51] offset:256
	v_add_u32_e32 v200, 0x98000, v182
	global_load_dwordx4 v[200:203], v200, s[8:9]
	v_add_u32_e32 v206, 0x98000, v182
	global_load_dwordx4 v[206:209], v206, s[8:9] offset:256
	v_add_u32_e32 v146, 0x10000, v184
	global_load_dwordx4 v[146:149], v146, s[50:51]
	v_add_u32_e32 v150, 0x10000, v184
	global_load_dwordx4 v[150:153], v150, s[50:51] offset:256
	v_add_u32_e32 v210, 0xe4000, v182
	global_load_dwordx4 v[210:213], v210, s[8:9]
	v_add_u32_e32 v214, 0xe4000, v182
	global_load_dwordx4 v[214:217], v214, s[8:9] offset:256
	v_add_u32_e32 v154, 0x18000, v184
	global_load_dwordx4 v[154:157], v154, s[50:51]
	v_add_u32_e32 v158, 0x18000, v184
	global_load_dwordx4 v[158:161], v158, s[50:51] offset:256
	s_mov_b32 s98, 0xbfb8aa3b
	s_mov_b32 s100, 1.0
	s_waitcnt vmcnt(12)
	v_lshlrev_b32_e32 v222, 16, v174
	v_and_b32_e32 v223, 0xffff0000, v174
	v_lshlrev_b32_e32 v224, 16, v175
	v_and_b32_e32 v225, 0xffff0000, v175
	v_lshlrev_b32_e32 v226, 16, v176
	v_and_b32_e32 v227, 0xffff0000, v176
	v_lshlrev_b32_e32 v228, 16, v177
	v_and_b32_e32 v229, 0xffff0000, v177
	v_pk_add_f32 v[222:223], v[162:163], v[222:223]
	v_pk_add_f32 v[224:225], v[164:165], v[224:225]
	v_pk_add_f32 v[226:227], v[166:167], v[226:227]
	v_pk_add_f32 v[228:229], v[168:169], v[228:229]
	v_pk_mul_f32 v[222:223], v[222:223], s[98:99] op_sel_hi:[1,0]
	v_pk_mul_f32 v[224:225], v[224:225], s[98:99] op_sel_hi:[1,0]
	v_pk_mul_f32 v[226:227], v[226:227], s[98:99] op_sel_hi:[1,0]
	v_pk_mul_f32 v[228:229], v[228:229], s[98:99] op_sel_hi:[1,0]
	v_exp_f32_e32 v222, v222
	v_exp_f32_e32 v223, v223
	v_exp_f32_e32 v224, v224
	v_exp_f32_e32 v225, v225
	v_exp_f32_e32 v226, v226
	v_exp_f32_e32 v227, v227
	v_exp_f32_e32 v228, v228
	v_exp_f32_e32 v229, v229
	v_pk_add_f32 v[222:223], v[222:223], s[100:101] op_sel_hi:[1,0]
	v_pk_add_f32 v[224:225], v[224:225], s[100:101] op_sel_hi:[1,0]
	v_pk_add_f32 v[226:227], v[226:227], s[100:101] op_sel_hi:[1,0]
	v_pk_add_f32 v[228:229], v[228:229], s[100:101] op_sel_hi:[1,0]
	v_rcp_f32_e32 v222, v222
	v_rcp_f32_e32 v223, v223
	v_rcp_f32_e32 v224, v224
	v_rcp_f32_e32 v225, v225
	v_rcp_f32_e32 v226, v226
	v_rcp_f32_e32 v227, v227
	v_rcp_f32_e32 v228, v228
	v_rcp_f32_e32 v229, v229
	v_pk_mul_f32 v[142:143], v[142:143], v[222:223]
	v_pk_mul_f32 v[144:145], v[144:145], v[224:225]
	v_pk_mul_f32 v[138:139], v[138:139], v[226:227]
	v_pk_mul_f32 v[140:141], v[140:141], v[228:229]
	v_lshlrev_b32_e32 v222, 16, v66
	v_and_b32_e32 v223, 0xffff0000, v66
	v_lshlrev_b32_e32 v224, 16, v67
	v_and_b32_e32 v225, 0xffff0000, v67
	v_lshlrev_b32_e32 v226, 16, v68
	v_and_b32_e32 v227, 0xffff0000, v68
	v_lshlrev_b32_e32 v228, 16, v69
	v_and_b32_e32 v229, 0xffff0000, v69
	v_pk_add_f32 v[142:143], v[142:143], v[222:223]
	v_pk_add_f32 v[144:145], v[144:145], v[224:225]
	v_pk_add_f32 v[138:139], v[138:139], v[226:227]
	v_pk_add_f32 v[140:141], v[140:141], v[228:229]
	v_cvt_pk_bf16_f32 v232, v142, v143
	v_cvt_pk_bf16_f32 v233, v144, v145
	v_cvt_pk_bf16_f32 v234, v138, v139
	v_cvt_pk_bf16_f32 v235, v140, v141
	v_lshlrev_b32_e32 v222, 16, v178
	v_and_b32_e32 v223, 0xffff0000, v178
	v_lshlrev_b32_e32 v224, 16, v179
	v_and_b32_e32 v225, 0xffff0000, v179
	v_lshlrev_b32_e32 v226, 16, v180
	v_and_b32_e32 v227, 0xffff0000, v180
	v_lshlrev_b32_e32 v228, 16, v181
	v_and_b32_e32 v229, 0xffff0000, v181
	v_pk_add_f32 v[222:223], v[170:171], v[222:223]
	v_pk_add_f32 v[224:225], v[172:173], v[224:225]
	v_pk_add_f32 v[226:227], v[218:219], v[226:227]
	v_pk_add_f32 v[228:229], v[220:221], v[228:229]
	v_pk_mul_f32 v[222:223], v[222:223], s[98:99] op_sel_hi:[1,0]
	v_pk_mul_f32 v[224:225], v[224:225], s[98:99] op_sel_hi:[1,0]
	v_pk_mul_f32 v[226:227], v[226:227], s[98:99] op_sel_hi:[1,0]
	v_pk_mul_f32 v[228:229], v[228:229], s[98:99] op_sel_hi:[1,0]
	v_exp_f32_e32 v222, v222
	v_exp_f32_e32 v223, v223
	v_exp_f32_e32 v224, v224
	v_exp_f32_e32 v225, v225
	v_exp_f32_e32 v226, v226
	v_exp_f32_e32 v227, v227
	v_exp_f32_e32 v228, v228
	v_exp_f32_e32 v229, v229
	v_pk_add_f32 v[222:223], v[222:223], s[100:101] op_sel_hi:[1,0]
	v_pk_add_f32 v[224:225], v[224:225], s[100:101] op_sel_hi:[1,0]
	v_pk_add_f32 v[226:227], v[226:227], s[100:101] op_sel_hi:[1,0]
	v_pk_add_f32 v[228:229], v[228:229], s[100:101] op_sel_hi:[1,0]
	v_rcp_f32_e32 v222, v222
	v_rcp_f32_e32 v223, v223
	v_rcp_f32_e32 v224, v224
	v_rcp_f32_e32 v225, v225
	v_rcp_f32_e32 v226, v226
	v_rcp_f32_e32 v227, v227
	v_rcp_f32_e32 v228, v228
	v_rcp_f32_e32 v229, v229
	v_pk_mul_f32 v[134:135], v[134:135], v[222:223]
	v_pk_mul_f32 v[136:137], v[136:137], v[224:225]
	v_pk_mul_f32 v[130:131], v[130:131], v[226:227]
	v_pk_mul_f32 v[132:133], v[132:133], v[228:229]
	v_lshlrev_b32_e32 v222, 16, v70
	v_and_b32_e32 v223, 0xffff0000, v70
	v_lshlrev_b32_e32 v224, 16, v71
	v_and_b32_e32 v225, 0xffff0000, v71
	v_lshlrev_b32_e32 v226, 16, v72
	v_and_b32_e32 v227, 0xffff0000, v72
	v_lshlrev_b32_e32 v228, 16, v73
	v_and_b32_e32 v229, 0xffff0000, v73
	v_pk_add_f32 v[134:135], v[134:135], v[222:223]
	v_pk_add_f32 v[136:137], v[136:137], v[224:225]
	v_pk_add_f32 v[130:131], v[130:131], v[226:227]
	v_pk_add_f32 v[132:133], v[132:133], v[228:229]
	v_cvt_pk_bf16_f32 v236, v134, v135
	v_cvt_pk_bf16_f32 v237, v136, v137
	v_cvt_pk_bf16_f32 v238, v130, v131
	v_cvt_pk_bf16_f32 v239, v132, v133
	v_add_u32_e32 v174, 0x260000, v182
	global_load_dwordx4 v[174:177], v174, s[8:9]
	v_add_u32_e32 v178, 0x260000, v182
	global_load_dwordx4 v[178:181], v178, s[8:9] offset:256
	v_add_u32_e32 v66, 0x40000, v184
	global_load_dwordx4 v[66:69], v66, s[50:51]
	v_add_u32_e32 v70, 0x40000, v184
	global_load_dwordx4 v[70:73], v70, s[50:51] offset:256
	global_store_dwordx4 v184, v[232:235], s[52:53]
	global_store_dwordx4 v184, v[236:239], s[52:53] offset:256
	s_waitcnt vmcnt(14)
; DI unsigned pk2(float lo, float hi) { unsigned r; asm("v_cvt_pk_bf16_f32 %0, %1, %2" : "=v"(r) : "v"(lo), "v"(hi)); return r; }
; DI float bflo(unsigned u) { return __uint_as_float(u << 16); }
; DI float bfhi(unsigned u) { return __uint_as_float(u & 0xffff0000u); }
; DI float fsigmoid(float x) { return frcp(1.0f + fexp2(-1.44269504f * x)); }
;     DI void operator()(const f32x4 (&acc)[2][2][4][2], const Unit& u, int wr, int wc, int fr, int fq) const {
;     ...
;                     for (int bj = 0; bj < 2; ++bj) { const int row = rowb + ai * HALF + (2 * mp + mm) * 16, col = col0 + bj * HALF;
;                         zg[mm][bj] = *(const u32x4*)(Zg + (size_t)row * INW + col);
;                         if (SECOND) yv[mm][bj] = *(const u32x4*)(Y1 + (size_t)row * D + col); }
;                 asm volatile("" ::: "memory");
; #pragma unroll
;                 for (int mm = 0; mm < 2; ++mm)
; #pragma unroll
;                     for (int bj = 0; bj < 2; ++bj) { const int m = 2 * mp + mm; const int row = rowb + ai * HALF + m * 16, col = col0 + bj * HALF;
;                         const u32x4 z = zg[mm][bj]; const f32x4 b0 = bb[bj][0], b1 = bb[bj][1];
;                         f32x4 g0, g1;
;                         g0[0] = fsigmoid(bflo(z.x) + b0[0]); g0[1] = fsigmoid(bfhi(z.x) + b0[1]); g0[2] = fsigmoid(bflo(z.y) + b0[2]); g0[3] = fsigmoid(bfhi(z.y) + b0[3]);
;                         g1[0] = fsigmoid(bflo(z.z) + b1[0]); g1[1] = fsigmoid(bfhi(z.z) + b1[1]); g1[2] = fsigmoid(bflo(z.w) + b1[2]); g1[3] = fsigmoid(bfhi(z.w) + b1[3]);
;                         f32x4 v0 = g0 * acc[ai][bj][m][0], v1 = g1 * acc[ai][bj][m][1];
;                         if (SECOND) { const u32x4 y = yv[mm][bj];
;                             v0[0] += bflo(y.x); v0[1] += bfhi(y.x); v0[2] += bflo(y.y); v0[3] += bfhi(y.y); v1[0] += bflo(y.z); v1[1] += bfhi(y.z); v1[2] += bflo(y.w); v1[3] += bfhi(y.w); }
;                         u32x4 w; w.x = pk2(v0[0], v0[1]); w.y = pk2(v0[2], v0[3]); w.z = pk2(v1[0], v1[1]); w.w = pk2(v1[2], v1[3]);
;                         *(u32x4*)((SECOND ? Mb : Y1) + (size_t)row * D + col) = w; }
	v_lshlrev_b32_e32 v222, 16, v186
	v_and_b32_e32 v223, 0xffff0000, v186
	v_lshlrev_b32_e32 v224, 16, v187
	v_and_b32_e32 v225, 0xffff0000, v187
	v_lshlrev_b32_e32 v226, 16, v188
	v_and_b32_e32 v227, 0xffff0000, v188
	v_lshlrev_b32_e32 v228, 16, v189
	v_and_b32_e32 v229, 0xffff0000, v189
	v_pk_add_f32 v[222:223], v[162:163], v[222:223]
	v_pk_add_f32 v[224:225], v[164:165], v[224:225]
	v_pk_add_f32 v[226:227], v[166:167], v[226:227]
	v_pk_add_f32 v[228:229], v[168:169], v[228:229]
	v_pk_mul_f32 v[222:223], v[222:223], s[98:99] op_sel_hi:[1,0]
	v_pk_mul_f32 v[224:225], v[224:225], s[98:99] op_sel_hi:[1,0]
	v_pk_mul_f32 v[226:227], v[226:227], s[98:99] op_sel_hi:[1,0]
	v_pk_mul_f32 v[228:229], v[228:229], s[98:99] op_sel_hi:[1,0]
	v_exp_f32_e32 v222, v222
	v_exp_f32_e32 v223, v223
	v_exp_f32_e32 v224, v224
	v_exp_f32_e32 v225, v225
	v_exp_f32_e32 v226, v226
	v_exp_f32_e32 v227, v227
	v_exp_f32_e32 v228, v228
	v_exp_f32_e32 v229, v229
	v_pk_add_f32 v[222:223], v[222:223], s[100:101] op_sel_hi:[1,0]
	v_pk_add_f32 v[224:225], v[224:225], s[100:101] op_sel_hi:[1,0]
	v_pk_add_f32 v[226:227], v[226:227], s[100:101] op_sel_hi:[1,0]
	v_pk_add_f32 v[228:229], v[228:229], s[100:101] op_sel_hi:[1,0]
	v_rcp_f32_e32 v222, v222
	v_rcp_f32_e32 v223, v223
	v_rcp_f32_e32 v224, v224
	v_rcp_f32_e32 v225, v225
	v_rcp_f32_e32 v226, v226
	v_rcp_f32_e32 v227, v227
	v_rcp_f32_e32 v228, v228
	v_rcp_f32_e32 v229, v229
	v_pk_mul_f32 v[126:127], v[126:127], v[222:223]
	v_pk_mul_f32 v[128:129], v[128:129], v[224:225]
	v_pk_mul_f32 v[122:123], v[122:123], v[226:227]
	v_pk_mul_f32 v[124:125], v[124:125], v[228:229]
	v_lshlrev_b32_e32 v222, 16, v82
	v_and_b32_e32 v223, 0xffff0000, v82
	v_lshlrev_b32_e32 v224, 16, v83
	v_and_b32_e32 v225, 0xffff0000, v83
	v_lshlrev_b32_e32 v226, 16, v84
	v_and_b32_e32 v227, 0xffff0000, v84
	v_lshlrev_b32_e32 v228, 16, v85
	v_and_b32_e32 v229, 0xffff0000, v85
	v_pk_add_f32 v[126:127], v[126:127], v[222:223]
	v_pk_add_f32 v[128:129], v[128:129], v[224:225]
	v_pk_add_f32 v[122:123], v[122:123], v[226:227]
	v_pk_add_f32 v[124:125], v[124:125], v[228:229]
	v_cvt_pk_bf16_f32 v232, v126, v127
	v_cvt_pk_bf16_f32 v233, v128, v129
	v_cvt_pk_bf16_f32 v234, v122, v123
	v_cvt_pk_bf16_f32 v235, v124, v125
	v_lshlrev_b32_e32 v222, 16, v190
	v_and_b32_e32 v223, 0xffff0000, v190
	v_lshlrev_b32_e32 v224, 16, v191
	v_and_b32_e32 v225, 0xffff0000, v191
	v_lshlrev_b32_e32 v226, 16, v192
	v_and_b32_e32 v227, 0xffff0000, v192
	v_lshlrev_b32_e32 v228, 16, v193
	v_and_b32_e32 v229, 0xffff0000, v193
	v_pk_add_f32 v[222:223], v[170:171], v[222:223]
	v_pk_add_f32 v[224:225], v[172:173], v[224:225]
	v_pk_add_f32 v[226:227], v[218:219], v[226:227]
	v_pk_add_f32 v[228:229], v[220:221], v[228:229]
	v_pk_mul_f32 v[222:223], v[222:223], s[98:99] op_sel_hi:[1,0]
	v_pk_mul_f32 v[224:225], v[224:225], s[98:99] op_sel_hi:[1,0]
	v_pk_mul_f32 v[226:227], v[226:227], s[98:99] op_sel_hi:[1,0]
	v_pk_mul_f32 v[228:229], v[228:229], s[98:99] op_sel_hi:[1,0]
	v_exp_f32_e32 v222, v222
	v_exp_f32_e32 v223, v223
	v_exp_f32_e32 v224, v224
	v_exp_f32_e32 v225, v225
	v_exp_f32_e32 v226, v226
	v_exp_f32_e32 v227, v227
	v_exp_f32_e32 v228, v228
	v_exp_f32_e32 v229, v229
	v_pk_add_f32 v[222:223], v[222:223], s[100:101] op_sel_hi:[1,0]
	v_pk_add_f32 v[224:225], v[224:225], s[100:101] op_sel_hi:[1,0]
	v_pk_add_f32 v[226:227], v[226:227], s[100:101] op_sel_hi:[1,0]
	v_pk_add_f32 v[228:229], v[228:229], s[100:101] op_sel_hi:[1,0]
	v_rcp_f32_e32 v222, v222
	v_rcp_f32_e32 v223, v223
	v_rcp_f32_e32 v224, v224
	v_rcp_f32_e32 v225, v225
	v_rcp_f32_e32 v226, v226
	v_rcp_f32_e32 v227, v227
	v_rcp_f32_e32 v228, v228
	v_rcp_f32_e32 v229, v229
	v_pk_mul_f32 v[118:119], v[118:119], v[222:223]
	v_pk_mul_f32 v[120:121], v[120:121], v[224:225]
	v_pk_mul_f32 v[114:115], v[114:115], v[226:227]
	v_pk_mul_f32 v[116:117], v[116:117], v[228:229]
	v_lshlrev_b32_e32 v222, 16, v86
	v_and_b32_e32 v223, 0xffff0000, v86
	v_lshlrev_b32_e32 v224, 16, v87
	v_and_b32_e32 v225, 0xffff0000, v87
	v_lshlrev_b32_e32 v226, 16, v88
	v_and_b32_e32 v227, 0xffff0000, v88
	v_lshlrev_b32_e32 v228, 16, v89
	v_and_b32_e32 v229, 0xffff0000, v89
	v_pk_add_f32 v[118:119], v[118:119], v[222:223]
	v_pk_add_f32 v[120:121], v[120:121], v[224:225]
	v_pk_add_f32 v[114:115], v[114:115], v[226:227]
	v_pk_add_f32 v[116:117], v[116:117], v[228:229]
	v_cvt_pk_bf16_f32 v236, v118, v119
	v_cvt_pk_bf16_f32 v237, v120, v121
	v_cvt_pk_bf16_f32 v238, v114, v115
	v_cvt_pk_bf16_f32 v239, v116, v117
	v_add_u32_e32 v186, 0x2ac000, v182
	global_load_dwordx4 v[186:189], v186, s[8:9]
	v_add_u32_e32 v190, 0x2ac000, v182
	global_load_dwordx4 v[190:193], v190, s[8:9] offset:256
	v_add_u32_e32 v82, 0x48000, v184
	global_load_dwordx4 v[82:85], v82, s[50:51]
	v_add_u32_e32 v86, 0x48000, v184
	global_load_dwordx4 v[86:89], v86, s[50:51] offset:256
	v_add_u32_e32 v195, 0x8000, v184
	global_store_dwordx4 v195, v[232:235], s[52:53]
	global_store_dwordx4 v195, v[236:239], s[52:53] offset:256
	s_waitcnt vmcnt(16)
; DI unsigned pk2(float lo, float hi) { unsigned r; asm("v_cvt_pk_bf16_f32 %0, %1, %2" : "=v"(r) : "v"(lo), "v"(hi)); return r; }
; DI float bflo(unsigned u) { return __uint_as_float(u << 16); }
; DI float bfhi(unsigned u) { return __uint_as_float(u & 0xffff0000u); }
; DI float fsigmoid(float x) { return frcp(1.0f + fexp2(-1.44269504f * x)); }
;     DI void operator()(const f32x4 (&acc)[2][2][4][2], const Unit& u, int wr, int wc, int fr, int fq) const {
;     ...
;                     for (int bj = 0; bj < 2; ++bj) { const int row = rowb + ai * HALF + (2 * mp + mm) * 16, col = col0 + bj * HALF;
;                         zg[mm][bj] = *(const u32x4*)(Zg + (size_t)row * INW + col);
;                         if (SECOND) yv[mm][bj] = *(const u32x4*)(Y1 + (size_t)row * D + col); }
;                 asm volatile("" ::: "memory");
; #pragma unroll
;                 for (int mm = 0; mm < 2; ++mm)
; #pragma unroll
;                     for (int bj = 0; bj < 2; ++bj) { const int m = 2 * mp + mm; const int row = rowb + ai * HALF + m * 16, col = col0 + bj * HALF;
;                         const u32x4 z = zg[mm][bj]; const f32x4 b0 = bb[bj][0], b1 = bb[bj][1];
;                         f32x4 g0, g1;
;                         g0[0] = fsigmoid(bflo(z.x) + b0[0]); g0[1] = fsigmoid(bfhi(z.x) + b0[1]); g0[2] = fsigmoid(bflo(z.y) + b0[2]); g0[3] = fsigmoid(bfhi(z.y) + b0[3]);
;                         g1[0] = fsigmoid(bflo(z.z) + b1[0]); g1[1] = fsigmoid(bfhi(z.z) + b1[1]); g1[2] = fsigmoid(bflo(z.w) + b1[2]); g1[3] = fsigmoid(bfhi(z.w) + b1[3]);
;                         f32x4 v0 = g0 * acc[ai][bj][m][0], v1 = g1 * acc[ai][bj][m][1];
;                         if (SECOND) { const u32x4 y = yv[mm][bj];
;                             v0[0] += bflo(y.x); v0[1] += bfhi(y.x); v0[2] += bflo(y.y); v0[3] += bfhi(y.y); v1[0] += bflo(y.z); v1[1] += bfhi(y.z); v1[2] += bflo(y.w); v1[3] += bfhi(y.w); }
;                         u32x4 w; w.x = pk2(v0[0], v0[1]); w.y = pk2(v0[2], v0[3]); w.z = pk2(v1[0], v1[1]); w.w = pk2(v1[2], v1[3]);
;                         *(u32x4*)((SECOND ? Mb : Y1) + (size_t)row * D + col) = w; }
	v_lshlrev_b32_e32 v222, 16, v200
	v_and_b32_e32 v223, 0xffff0000, v200
	v_lshlrev_b32_e32 v224, 16, v201
	v_and_b32_e32 v225, 0xffff0000, v201
	v_lshlrev_b32_e32 v226, 16, v202
	v_and_b32_e32 v227, 0xffff0000, v202
	v_lshlrev_b32_e32 v228, 16, v203
	v_and_b32_e32 v229, 0xffff0000, v203
	v_pk_add_f32 v[222:223], v[162:163], v[222:223]
	v_pk_add_f32 v[224:225], v[164:165], v[224:225]
	v_pk_add_f32 v[226:227], v[166:167], v[226:227]
	v_pk_add_f32 v[228:229], v[168:169], v[228:229]
	v_pk_mul_f32 v[222:223], v[222:223], s[98:99] op_sel_hi:[1,0]
	v_pk_mul_f32 v[224:225], v[224:225], s[98:99] op_sel_hi:[1,0]
	v_pk_mul_f32 v[226:227], v[226:227], s[98:99] op_sel_hi:[1,0]
	v_pk_mul_f32 v[228:229], v[228:229], s[98:99] op_sel_hi:[1,0]
	v_exp_f32_e32 v222, v222
	v_exp_f32_e32 v223, v223
	v_exp_f32_e32 v224, v224
	v_exp_f32_e32 v225, v225
	v_exp_f32_e32 v226, v226
	v_exp_f32_e32 v227, v227
	v_exp_f32_e32 v228, v228
	v_exp_f32_e32 v229, v229
	v_pk_add_f32 v[222:223], v[222:223], s[100:101] op_sel_hi:[1,0]
	v_pk_add_f32 v[224:225], v[224:225], s[100:101] op_sel_hi:[1,0]
	v_pk_add_f32 v[226:227], v[226:227], s[100:101] op_sel_hi:[1,0]
	v_pk_add_f32 v[228:229], v[228:229], s[100:101] op_sel_hi:[1,0]
	v_rcp_f32_e32 v222, v222
	v_rcp_f32_e32 v223, v223
	v_rcp_f32_e32 v224, v224
	v_rcp_f32_e32 v225, v225
	v_rcp_f32_e32 v226, v226
	v_rcp_f32_e32 v227, v227
	v_rcp_f32_e32 v228, v228
	v_rcp_f32_e32 v229, v229
	v_pk_mul_f32 v[110:111], v[110:111], v[222:223]
	v_pk_mul_f32 v[112:113], v[112:113], v[224:225]
	v_pk_mul_f32 v[106:107], v[106:107], v[226:227]
	v_pk_mul_f32 v[108:109], v[108:109], v[228:229]
	v_lshlrev_b32_e32 v222, 16, v146
	v_and_b32_e32 v223, 0xffff0000, v146
	v_lshlrev_b32_e32 v224, 16, v147
	v_and_b32_e32 v225, 0xffff0000, v147
	v_lshlrev_b32_e32 v226, 16, v148
	v_and_b32_e32 v227, 0xffff0000, v148
	v_lshlrev_b32_e32 v228, 16, v149
	v_and_b32_e32 v229, 0xffff0000, v149
	v_pk_add_f32 v[110:111], v[110:111], v[222:223]
	v_pk_add_f32 v[112:113], v[112:113], v[224:225]
	v_pk_add_f32 v[106:107], v[106:107], v[226:227]
	v_pk_add_f32 v[108:109], v[108:109], v[228:229]
	v_cvt_pk_bf16_f32 v232, v110, v111
	v_cvt_pk_bf16_f32 v233, v112, v113
	v_cvt_pk_bf16_f32 v234, v106, v107
	v_cvt_pk_bf16_f32 v235, v108, v109
	v_lshlrev_b32_e32 v222, 16, v206
	v_and_b32_e32 v223, 0xffff0000, v206
	v_lshlrev_b32_e32 v224, 16, v207
	v_and_b32_e32 v225, 0xffff0000, v207
	v_lshlrev_b32_e32 v226, 16, v208
	v_and_b32_e32 v227, 0xffff0000, v208
	v_lshlrev_b32_e32 v228, 16, v209
	v_and_b32_e32 v229, 0xffff0000, v209
	v_pk_add_f32 v[222:223], v[170:171], v[222:223]
	v_pk_add_f32 v[224:225], v[172:173], v[224:225]
	v_pk_add_f32 v[226:227], v[218:219], v[226:227]
	v_pk_add_f32 v[228:229], v[220:221], v[228:229]
	v_pk_mul_f32 v[222:223], v[222:223], s[98:99] op_sel_hi:[1,0]
	v_pk_mul_f32 v[224:225], v[224:225], s[98:99] op_sel_hi:[1,0]
	v_pk_mul_f32 v[226:227], v[226:227], s[98:99] op_sel_hi:[1,0]
	v_pk_mul_f32 v[228:229], v[228:229], s[98:99] op_sel_hi:[1,0]
	v_exp_f32_e32 v222, v222
	v_exp_f32_e32 v223, v223
	v_exp_f32_e32 v224, v224
	v_exp_f32_e32 v225, v225
	v_exp_f32_e32 v226, v226
	v_exp_f32_e32 v227, v227
	v_exp_f32_e32 v228, v228
	v_exp_f32_e32 v229, v229
	v_pk_add_f32 v[222:223], v[222:223], s[100:101] op_sel_hi:[1,0]
	v_pk_add_f32 v[224:225], v[224:225], s[100:101] op_sel_hi:[1,0]
	v_pk_add_f32 v[226:227], v[226:227], s[100:101] op_sel_hi:[1,0]
	v_pk_add_f32 v[228:229], v[228:229], s[100:101] op_sel_hi:[1,0]
	v_rcp_f32_e32 v222, v222
	v_rcp_f32_e32 v223, v223
	v_rcp_f32_e32 v224, v224
	v_rcp_f32_e32 v225, v225
	v_rcp_f32_e32 v226, v226
	v_rcp_f32_e32 v227, v227
	v_rcp_f32_e32 v228, v228
	v_rcp_f32_e32 v229, v229
	v_pk_mul_f32 v[102:103], v[102:103], v[222:223]
	v_pk_mul_f32 v[104:105], v[104:105], v[224:225]
	v_pk_mul_f32 v[98:99], v[98:99], v[226:227]
	v_pk_mul_f32 v[100:101], v[100:101], v[228:229]
	v_lshlrev_b32_e32 v222, 16, v150
	v_and_b32_e32 v223, 0xffff0000, v150
	v_lshlrev_b32_e32 v224, 16, v151
	v_and_b32_e32 v225, 0xffff0000, v151
	v_lshlrev_b32_e32 v226, 16, v152
	v_and_b32_e32 v227, 0xffff0000, v152
	v_lshlrev_b32_e32 v228, 16, v153
	v_and_b32_e32 v229, 0xffff0000, v153
	v_pk_add_f32 v[102:103], v[102:103], v[222:223]
	v_pk_add_f32 v[104:105], v[104:105], v[224:225]
	v_pk_add_f32 v[98:99], v[98:99], v[226:227]
	v_pk_add_f32 v[100:101], v[100:101], v[228:229]
	v_cvt_pk_bf16_f32 v236, v102, v103
	v_cvt_pk_bf16_f32 v237, v104, v105
	v_cvt_pk_bf16_f32 v238, v98, v99
	v_cvt_pk_bf16_f32 v239, v100, v101
	v_add_u32_e32 v200, 0x2f8000, v182
	global_load_dwordx4 v[200:203], v200, s[8:9]
	v_add_u32_e32 v206, 0x2f8000, v182
	global_load_dwordx4 v[206:209], v206, s[8:9] offset:256
	v_add_u32_e32 v146, 0x50000, v184
	global_load_dwordx4 v[146:149], v146, s[50:51]
	v_add_u32_e32 v150, 0x50000, v184
	global_load_dwordx4 v[150:153], v150, s[50:51] offset:256
	v_add_u32_e32 v195, 0x10000, v184
	global_store_dwordx4 v195, v[232:235], s[52:53]
	global_store_dwordx4 v195, v[236:239], s[52:53] offset:256
	s_waitcnt vmcnt(18)
; DI unsigned pk2(float lo, float hi) { unsigned r; asm("v_cvt_pk_bf16_f32 %0, %1, %2" : "=v"(r) : "v"(lo), "v"(hi)); return r; }
; DI float bflo(unsigned u) { return __uint_as_float(u << 16); }
; DI float bfhi(unsigned u) { return __uint_as_float(u & 0xffff0000u); }
; DI float fsigmoid(float x) { return frcp(1.0f + fexp2(-1.44269504f * x)); }
;     DI void operator()(const f32x4 (&acc)[2][2][4][2], const Unit& u, int wr, int wc, int fr, int fq) const {
;     ...
;                     for (int bj = 0; bj < 2; ++bj) { const int row = rowb + ai * HALF + (2 * mp + mm) * 16, col = col0 + bj * HALF;
;                         zg[mm][bj] = *(const u32x4*)(Zg + (size_t)row * INW + col);
;                         if (SECOND) yv[mm][bj] = *(const u32x4*)(Y1 + (size_t)row * D + col); }
;                 asm volatile("" ::: "memory");
; #pragma unroll
;                 for (int mm = 0; mm < 2; ++mm)
; #pragma unroll
;                     for (int bj = 0; bj < 2; ++bj) { const int m = 2 * mp + mm; const int row = rowb + ai * HALF + m * 16, col = col0 + bj * HALF;
;                         const u32x4 z = zg[mm][bj]; const f32x4 b0 = bb[bj][0], b1 = bb[bj][1];
;                         f32x4 g0, g1;
;                         g0[0] = fsigmoid(bflo(z.x) + b0[0]); g0[1] = fsigmoid(bfhi(z.x) + b0[1]); g0[2] = fsigmoid(bflo(z.y) + b0[2]); g0[3] = fsigmoid(bfhi(z.y) + b0[3]);
;                         g1[0] = fsigmoid(bflo(z.z) + b1[0]); g1[1] = fsigmoid(bfhi(z.z) + b1[1]); g1[2] = fsigmoid(bflo(z.w) + b1[2]); g1[3] = fsigmoid(bfhi(z.w) + b1[3]);
;                         f32x4 v0 = g0 * acc[ai][bj][m][0], v1 = g1 * acc[ai][bj][m][1];
;                         if (SECOND) { const u32x4 y = yv[mm][bj];
;                             v0[0] += bflo(y.x); v0[1] += bfhi(y.x); v0[2] += bflo(y.y); v0[3] += bfhi(y.y); v1[0] += bflo(y.z); v1[1] += bfhi(y.z); v1[2] += bflo(y.w); v1[3] += bfhi(y.w); }
;                         u32x4 w; w.x = pk2(v0[0], v0[1]); w.y = pk2(v0[2], v0[3]); w.z = pk2(v1[0], v1[1]); w.w = pk2(v1[2], v1[3]);
;                         *(u32x4*)((SECOND ? Mb : Y1) + (size_t)row * D + col) = w; }
	v_lshlrev_b32_e32 v222, 16, v210
	v_and_b32_e32 v223, 0xffff0000, v210
	v_lshlrev_b32_e32 v224, 16, v211
	v_and_b32_e32 v225, 0xffff0000, v211
	v_lshlrev_b32_e32 v226, 16, v212
	v_and_b32_e32 v227, 0xffff0000, v212
	v_lshlrev_b32_e32 v228, 16, v213
	v_and_b32_e32 v229, 0xffff0000, v213
	v_pk_add_f32 v[222:223], v[162:163], v[222:223]
	v_pk_add_f32 v[224:225], v[164:165], v[224:225]
	v_pk_add_f32 v[226:227], v[166:167], v[226:227]
	v_pk_add_f32 v[228:229], v[168:169], v[228:229]
	v_pk_mul_f32 v[222:223], v[222:223], s[98:99] op_sel_hi:[1,0]
	v_pk_mul_f32 v[224:225], v[224:225], s[98:99] op_sel_hi:[1,0]
	v_pk_mul_f32 v[226:227], v[226:227], s[98:99] op_sel_hi:[1,0]
	v_pk_mul_f32 v[228:229], v[228:229], s[98:99] op_sel_hi:[1,0]
	v_exp_f32_e32 v222, v222
	v_exp_f32_e32 v223, v223
	v_exp_f32_e32 v224, v224
	v_exp_f32_e32 v225, v225
	v_exp_f32_e32 v226, v226
	v_exp_f32_e32 v227, v227
	v_exp_f32_e32 v228, v228
	v_exp_f32_e32 v229, v229
	v_pk_add_f32 v[222:223], v[222:223], s[100:101] op_sel_hi:[1,0]
	v_pk_add_f32 v[224:225], v[224:225], s[100:101] op_sel_hi:[1,0]
	v_pk_add_f32 v[226:227], v[226:227], s[100:101] op_sel_hi:[1,0]
	v_pk_add_f32 v[228:229], v[228:229], s[100:101] op_sel_hi:[1,0]
	v_rcp_f32_e32 v222, v222
	v_rcp_f32_e32 v223, v223
	v_rcp_f32_e32 v224, v224
	v_rcp_f32_e32 v225, v225
	v_rcp_f32_e32 v226, v226
	v_rcp_f32_e32 v227, v227
	v_rcp_f32_e32 v228, v228
	v_rcp_f32_e32 v229, v229
	v_pk_mul_f32 v[94:95], v[94:95], v[222:223]
	v_pk_mul_f32 v[96:97], v[96:97], v[224:225]
	v_pk_mul_f32 v[90:91], v[90:91], v[226:227]
	v_pk_mul_f32 v[92:93], v[92:93], v[228:229]
	v_lshlrev_b32_e32 v222, 16, v154
	v_and_b32_e32 v223, 0xffff0000, v154
	v_lshlrev_b32_e32 v224, 16, v155
	v_and_b32_e32 v225, 0xffff0000, v155
	v_lshlrev_b32_e32 v226, 16, v156
	v_and_b32_e32 v227, 0xffff0000, v156
	v_lshlrev_b32_e32 v228, 16, v157
	v_and_b32_e32 v229, 0xffff0000, v157
	v_pk_add_f32 v[94:95], v[94:95], v[222:223]
	v_pk_add_f32 v[96:97], v[96:97], v[224:225]
	v_pk_add_f32 v[90:91], v[90:91], v[226:227]
	v_pk_add_f32 v[92:93], v[92:93], v[228:229]
	v_cvt_pk_bf16_f32 v232, v94, v95
	v_cvt_pk_bf16_f32 v233, v96, v97
	v_cvt_pk_bf16_f32 v234, v90, v91
	v_cvt_pk_bf16_f32 v235, v92, v93
	v_lshlrev_b32_e32 v222, 16, v214
	v_and_b32_e32 v223, 0xffff0000, v214
	v_lshlrev_b32_e32 v224, 16, v215
	v_and_b32_e32 v225, 0xffff0000, v215
	v_lshlrev_b32_e32 v226, 16, v216
	v_and_b32_e32 v227, 0xffff0000, v216
	v_lshlrev_b32_e32 v228, 16, v217
	v_and_b32_e32 v229, 0xffff0000, v217
	v_pk_add_f32 v[222:223], v[170:171], v[222:223]
	v_pk_add_f32 v[224:225], v[172:173], v[224:225]
	v_pk_add_f32 v[226:227], v[218:219], v[226:227]
	v_pk_add_f32 v[228:229], v[220:221], v[228:229]
	v_pk_mul_f32 v[222:223], v[222:223], s[98:99] op_sel_hi:[1,0]
	v_pk_mul_f32 v[224:225], v[224:225], s[98:99] op_sel_hi:[1,0]
	v_pk_mul_f32 v[226:227], v[226:227], s[98:99] op_sel_hi:[1,0]
	v_pk_mul_f32 v[228:229], v[228:229], s[98:99] op_sel_hi:[1,0]
	v_exp_f32_e32 v222, v222
	v_exp_f32_e32 v223, v223
	v_exp_f32_e32 v224, v224
	v_exp_f32_e32 v225, v225
	v_exp_f32_e32 v226, v226
	v_exp_f32_e32 v227, v227
	v_exp_f32_e32 v228, v228
	v_exp_f32_e32 v229, v229
	v_pk_add_f32 v[222:223], v[222:223], s[100:101] op_sel_hi:[1,0]
	v_pk_add_f32 v[224:225], v[224:225], s[100:101] op_sel_hi:[1,0]
	v_pk_add_f32 v[226:227], v[226:227], s[100:101] op_sel_hi:[1,0]
	v_pk_add_f32 v[228:229], v[228:229], s[100:101] op_sel_hi:[1,0]
	v_rcp_f32_e32 v222, v222
	v_rcp_f32_e32 v223, v223
	v_rcp_f32_e32 v224, v224
	v_rcp_f32_e32 v225, v225
	v_rcp_f32_e32 v226, v226
	v_rcp_f32_e32 v227, v227
	v_rcp_f32_e32 v228, v228
	v_rcp_f32_e32 v229, v229
	v_pk_mul_f32 v[78:79], v[78:79], v[222:223]
	v_pk_mul_f32 v[80:81], v[80:81], v[224:225]
	v_pk_mul_f32 v[74:75], v[74:75], v[226:227]
	v_pk_mul_f32 v[76:77], v[76:77], v[228:229]
	v_lshlrev_b32_e32 v222, 16, v158
	v_and_b32_e32 v223, 0xffff0000, v158
	v_lshlrev_b32_e32 v224, 16, v159
	v_and_b32_e32 v225, 0xffff0000, v159
	v_lshlrev_b32_e32 v226, 16, v160
	v_and_b32_e32 v227, 0xffff0000, v160
	v_lshlrev_b32_e32 v228, 16, v161
	v_and_b32_e32 v229, 0xffff0000, v161
	v_pk_add_f32 v[78:79], v[78:79], v[222:223]
	v_pk_add_f32 v[80:81], v[80:81], v[224:225]
	v_pk_add_f32 v[74:75], v[74:75], v[226:227]
	v_pk_add_f32 v[76:77], v[76:77], v[228:229]
	v_cvt_pk_bf16_f32 v236, v78, v79
	v_cvt_pk_bf16_f32 v237, v80, v81
	v_cvt_pk_bf16_f32 v238, v74, v75
	v_cvt_pk_bf16_f32 v239, v76, v77
	v_add_u32_e32 v210, 0x344000, v182
	global_load_dwordx4 v[210:213], v210, s[8:9]
	v_add_u32_e32 v214, 0x344000, v182
	global_load_dwordx4 v[214:217], v214, s[8:9] offset:256
	v_add_u32_e32 v154, 0x58000, v184
	global_load_dwordx4 v[154:157], v154, s[50:51]
	v_add_u32_e32 v158, 0x58000, v184
	global_load_dwordx4 v[158:161], v158, s[50:51] offset:256
	v_add_u32_e32 v195, 0x18000, v184
	global_store_dwordx4 v195, v[232:235], s[52:53]
	global_store_dwordx4 v195, v[236:239], s[52:53] offset:256
	s_waitcnt vmcnt(20)
; DI unsigned pk2(float lo, float hi) { unsigned r; asm("v_cvt_pk_bf16_f32 %0, %1, %2" : "=v"(r) : "v"(lo), "v"(hi)); return r; }
; DI float bflo(unsigned u) { return __uint_as_float(u << 16); }
; DI float bfhi(unsigned u) { return __uint_as_float(u & 0xffff0000u); }
; DI float fsigmoid(float x) { return frcp(1.0f + fexp2(-1.44269504f * x)); }
;     DI void operator()(const f32x4 (&acc)[2][2][4][2], const Unit& u, int wr, int wc, int fr, int fq) const {
;     ...
;                     for (int bj = 0; bj < 2; ++bj) { const int row = rowb + ai * HALF + (2 * mp + mm) * 16, col = col0 + bj * HALF;
;                         zg[mm][bj] = *(const u32x4*)(Zg + (size_t)row * INW + col);
;                         if (SECOND) yv[mm][bj] = *(const u32x4*)(Y1 + (size_t)row * D + col); }
;                 asm volatile("" ::: "memory");
; #pragma unroll
;                 for (int mm = 0; mm < 2; ++mm)
; #pragma unroll
;                     for (int bj = 0; bj < 2; ++bj) { const int m = 2 * mp + mm; const int row = rowb + ai * HALF + m * 16, col = col0 + bj * HALF;
;                         const u32x4 z = zg[mm][bj]; const f32x4 b0 = bb[bj][0], b1 = bb[bj][1];
;                         f32x4 g0, g1;
;                         g0[0] = fsigmoid(bflo(z.x) + b0[0]); g0[1] = fsigmoid(bfhi(z.x) + b0[1]); g0[2] = fsigmoid(bflo(z.y) + b0[2]); g0[3] = fsigmoid(bfhi(z.y) + b0[3]);
;                         g1[0] = fsigmoid(bflo(z.z) + b1[0]); g1[1] = fsigmoid(bfhi(z.z) + b1[1]); g1[2] = fsigmoid(bflo(z.w) + b1[2]); g1[3] = fsigmoid(bfhi(z.w) + b1[3]);
;                         f32x4 v0 = g0 * acc[ai][bj][m][0], v1 = g1 * acc[ai][bj][m][1];
;                         if (SECOND) { const u32x4 y = yv[mm][bj];
;                             v0[0] += bflo(y.x); v0[1] += bfhi(y.x); v0[2] += bflo(y.y); v0[3] += bfhi(y.y); v1[0] += bflo(y.z); v1[1] += bfhi(y.z); v1[2] += bflo(y.w); v1[3] += bfhi(y.w); }
;                         u32x4 w; w.x = pk2(v0[0], v0[1]); w.y = pk2(v0[2], v0[3]); w.z = pk2(v1[0], v1[1]); w.w = pk2(v1[2], v1[3]);
;                         *(u32x4*)((SECOND ? Mb : Y1) + (size_t)row * D + col) = w; }
	v_lshlrev_b32_e32 v222, 16, v174
	v_and_b32_e32 v223, 0xffff0000, v174
	v_lshlrev_b32_e32 v224, 16, v175
	v_and_b32_e32 v225, 0xffff0000, v175
	v_lshlrev_b32_e32 v226, 16, v176
	v_and_b32_e32 v227, 0xffff0000, v176
	v_lshlrev_b32_e32 v228, 16, v177
	v_and_b32_e32 v229, 0xffff0000, v177
	v_pk_add_f32 v[222:223], v[162:163], v[222:223]
	v_pk_add_f32 v[224:225], v[164:165], v[224:225]
	v_pk_add_f32 v[226:227], v[166:167], v[226:227]
	v_pk_add_f32 v[228:229], v[168:169], v[228:229]
	v_pk_mul_f32 v[222:223], v[222:223], s[98:99] op_sel_hi:[1,0]
	v_pk_mul_f32 v[224:225], v[224:225], s[98:99] op_sel_hi:[1,0]
	v_pk_mul_f32 v[226:227], v[226:227], s[98:99] op_sel_hi:[1,0]
	v_pk_mul_f32 v[228:229], v[228:229], s[98:99] op_sel_hi:[1,0]
	v_exp_f32_e32 v222, v222
	v_exp_f32_e32 v223, v223
	v_exp_f32_e32 v224, v224
	v_exp_f32_e32 v225, v225
	v_exp_f32_e32 v226, v226
	v_exp_f32_e32 v227, v227
	v_exp_f32_e32 v228, v228
	v_exp_f32_e32 v229, v229
	v_pk_add_f32 v[222:223], v[222:223], s[100:101] op_sel_hi:[1,0]
	v_pk_add_f32 v[224:225], v[224:225], s[100:101] op_sel_hi:[1,0]
	v_pk_add_f32 v[226:227], v[226:227], s[100:101] op_sel_hi:[1,0]
	v_pk_add_f32 v[228:229], v[228:229], s[100:101] op_sel_hi:[1,0]
	v_rcp_f32_e32 v222, v222
	v_rcp_f32_e32 v223, v223
	v_rcp_f32_e32 v224, v224
	v_rcp_f32_e32 v225, v225
	v_rcp_f32_e32 v226, v226
	v_rcp_f32_e32 v227, v227
	v_rcp_f32_e32 v228, v228
	v_rcp_f32_e32 v229, v229
	v_pk_mul_f32 v[62:63], v[62:63], v[222:223]
	v_pk_mul_f32 v[64:65], v[64:65], v[224:225]
	v_pk_mul_f32 v[58:59], v[58:59], v[226:227]
	v_pk_mul_f32 v[60:61], v[60:61], v[228:229]
	v_lshlrev_b32_e32 v222, 16, v66
	v_and_b32_e32 v223, 0xffff0000, v66
	v_lshlrev_b32_e32 v224, 16, v67
	v_and_b32_e32 v225, 0xffff0000, v67
	v_lshlrev_b32_e32 v226, 16, v68
	v_and_b32_e32 v227, 0xffff0000, v68
	v_lshlrev_b32_e32 v228, 16, v69
	v_and_b32_e32 v229, 0xffff0000, v69
	v_pk_add_f32 v[62:63], v[62:63], v[222:223]
	v_pk_add_f32 v[64:65], v[64:65], v[224:225]
	v_pk_add_f32 v[58:59], v[58:59], v[226:227]
	v_pk_add_f32 v[60:61], v[60:61], v[228:229]
	v_cvt_pk_bf16_f32 v232, v62, v63
	v_cvt_pk_bf16_f32 v233, v64, v65
	v_cvt_pk_bf16_f32 v234, v58, v59
	v_cvt_pk_bf16_f32 v235, v60, v61
	v_lshlrev_b32_e32 v222, 16, v178
	v_and_b32_e32 v223, 0xffff0000, v178
	v_lshlrev_b32_e32 v224, 16, v179
	v_and_b32_e32 v225, 0xffff0000, v179
	v_lshlrev_b32_e32 v226, 16, v180
	v_and_b32_e32 v227, 0xffff0000, v180
	v_lshlrev_b32_e32 v228, 16, v181
	v_and_b32_e32 v229, 0xffff0000, v181
	v_pk_add_f32 v[222:223], v[170:171], v[222:223]
	v_pk_add_f32 v[224:225], v[172:173], v[224:225]
	v_pk_add_f32 v[226:227], v[218:219], v[226:227]
	v_pk_add_f32 v[228:229], v[220:221], v[228:229]
	v_pk_mul_f32 v[222:223], v[222:223], s[98:99] op_sel_hi:[1,0]
	v_pk_mul_f32 v[224:225], v[224:225], s[98:99] op_sel_hi:[1,0]
	v_pk_mul_f32 v[226:227], v[226:227], s[98:99] op_sel_hi:[1,0]
	v_pk_mul_f32 v[228:229], v[228:229], s[98:99] op_sel_hi:[1,0]
	v_exp_f32_e32 v222, v222
	v_exp_f32_e32 v223, v223
	v_exp_f32_e32 v224, v224
	v_exp_f32_e32 v225, v225
	v_exp_f32_e32 v226, v226
	v_exp_f32_e32 v227, v227
	v_exp_f32_e32 v228, v228
	v_exp_f32_e32 v229, v229
	v_pk_add_f32 v[222:223], v[222:223], s[100:101] op_sel_hi:[1,0]
	v_pk_add_f32 v[224:225], v[224:225], s[100:101] op_sel_hi:[1,0]
	v_pk_add_f32 v[226:227], v[226:227], s[100:101] op_sel_hi:[1,0]
	v_pk_add_f32 v[228:229], v[228:229], s[100:101] op_sel_hi:[1,0]
	v_rcp_f32_e32 v222, v222
	v_rcp_f32_e32 v223, v223
	v_rcp_f32_e32 v224, v224
	v_rcp_f32_e32 v225, v225
	v_rcp_f32_e32 v226, v226
	v_rcp_f32_e32 v227, v227
	v_rcp_f32_e32 v228, v228
	v_rcp_f32_e32 v229, v229
	v_pk_mul_f32 v[54:55], v[54:55], v[222:223]
	v_pk_mul_f32 v[56:57], v[56:57], v[224:225]
	v_pk_mul_f32 v[50:51], v[50:51], v[226:227]
	v_pk_mul_f32 v[52:53], v[52:53], v[228:229]
	v_lshlrev_b32_e32 v222, 16, v70
	v_and_b32_e32 v223, 0xffff0000, v70
	v_lshlrev_b32_e32 v224, 16, v71
	v_and_b32_e32 v225, 0xffff0000, v71
	v_lshlrev_b32_e32 v226, 16, v72
	v_and_b32_e32 v227, 0xffff0000, v72
	v_lshlrev_b32_e32 v228, 16, v73
	v_and_b32_e32 v229, 0xffff0000, v73
	v_pk_add_f32 v[54:55], v[54:55], v[222:223]
	v_pk_add_f32 v[56:57], v[56:57], v[224:225]
	v_pk_add_f32 v[50:51], v[50:51], v[226:227]
	v_pk_add_f32 v[52:53], v[52:53], v[228:229]
	v_cvt_pk_bf16_f32 v236, v54, v55
	v_cvt_pk_bf16_f32 v237, v56, v57
	v_cvt_pk_bf16_f32 v238, v50, v51
	v_cvt_pk_bf16_f32 v239, v52, v53
	v_add_u32_e32 v195, 0x40000, v184
	global_store_dwordx4 v195, v[232:235], s[52:53]
	global_store_dwordx4 v195, v[236:239], s[52:53] offset:256
	s_waitcnt vmcnt(16)
; DI unsigned pk2(float lo, float hi) { unsigned r; asm("v_cvt_pk_bf16_f32 %0, %1, %2" : "=v"(r) : "v"(lo), "v"(hi)); return r; }
; DI float bflo(unsigned u) { return __uint_as_float(u << 16); }
; DI float bfhi(unsigned u) { return __uint_as_float(u & 0xffff0000u); }
; DI float fsigmoid(float x) { return frcp(1.0f + fexp2(-1.44269504f * x)); }
;     DI void operator()(const f32x4 (&acc)[2][2][4][2], const Unit& u, int wr, int wc, int fr, int fq) const {
;     ...
;                     for (int bj = 0; bj < 2; ++bj) { const int row = rowb + ai * HALF + (2 * mp + mm) * 16, col = col0 + bj * HALF;
;                         zg[mm][bj] = *(const u32x4*)(Zg + (size_t)row * INW + col);
;                         if (SECOND) yv[mm][bj] = *(const u32x4*)(Y1 + (size_t)row * D + col); }
;                 asm volatile("" ::: "memory");
; #pragma unroll
;                 for (int mm = 0; mm < 2; ++mm)
; #pragma unroll
;                     for (int bj = 0; bj < 2; ++bj) { const int m = 2 * mp + mm; const int row = rowb + ai * HALF + m * 16, col = col0 + bj * HALF;
;                         const u32x4 z = zg[mm][bj]; const f32x4 b0 = bb[bj][0], b1 = bb[bj][1];
;                         f32x4 g0, g1;
;                         g0[0] = fsigmoid(bflo(z.x) + b0[0]); g0[1] = fsigmoid(bfhi(z.x) + b0[1]); g0[2] = fsigmoid(bflo(z.y) + b0[2]); g0[3] = fsigmoid(bfhi(z.y) + b0[3]);
;                         g1[0] = fsigmoid(bflo(z.z) + b1[0]); g1[1] = fsigmoid(bfhi(z.z) + b1[1]); g1[2] = fsigmoid(bflo(z.w) + b1[2]); g1[3] = fsigmoid(bfhi(z.w) + b1[3]);
;                         f32x4 v0 = g0 * acc[ai][bj][m][0], v1 = g1 * acc[ai][bj][m][1];
;                         if (SECOND) { const u32x4 y = yv[mm][bj];
;                             v0[0] += bflo(y.x); v0[1] += bfhi(y.x); v0[2] += bflo(y.y); v0[3] += bfhi(y.y); v1[0] += bflo(y.z); v1[1] += bfhi(y.z); v1[2] += bflo(y.w); v1[3] += bfhi(y.w); }
;                         u32x4 w; w.x = pk2(v0[0], v0[1]); w.y = pk2(v0[2], v0[3]); w.z = pk2(v1[0], v1[1]); w.w = pk2(v1[2], v1[3]);
;                         *(u32x4*)((SECOND ? Mb : Y1) + (size_t)row * D + col) = w; }
	v_lshlrev_b32_e32 v222, 16, v186
	v_and_b32_e32 v223, 0xffff0000, v186
	v_lshlrev_b32_e32 v224, 16, v187
	v_and_b32_e32 v225, 0xffff0000, v187
	v_lshlrev_b32_e32 v226, 16, v188
	v_and_b32_e32 v227, 0xffff0000, v188
	v_lshlrev_b32_e32 v228, 16, v189
	v_and_b32_e32 v229, 0xffff0000, v189
	v_pk_add_f32 v[222:223], v[162:163], v[222:223]
	v_pk_add_f32 v[224:225], v[164:165], v[224:225]
	v_pk_add_f32 v[226:227], v[166:167], v[226:227]
	v_pk_add_f32 v[228:229], v[168:169], v[228:229]
	v_pk_mul_f32 v[222:223], v[222:223], s[98:99] op_sel_hi:[1,0]
	v_pk_mul_f32 v[224:225], v[224:225], s[98:99] op_sel_hi:[1,0]
	v_pk_mul_f32 v[226:227], v[226:227], s[98:99] op_sel_hi:[1,0]
	v_pk_mul_f32 v[228:229], v[228:229], s[98:99] op_sel_hi:[1,0]
	v_exp_f32_e32 v222, v222
	v_exp_f32_e32 v223, v223
	v_exp_f32_e32 v224, v224
	v_exp_f32_e32 v225, v225
	v_exp_f32_e32 v226, v226
	v_exp_f32_e32 v227, v227
	v_exp_f32_e32 v228, v228
	v_exp_f32_e32 v229, v229
	v_pk_add_f32 v[222:223], v[222:223], s[100:101] op_sel_hi:[1,0]
	v_pk_add_f32 v[224:225], v[224:225], s[100:101] op_sel_hi:[1,0]
	v_pk_add_f32 v[226:227], v[226:227], s[100:101] op_sel_hi:[1,0]
	v_pk_add_f32 v[228:229], v[228:229], s[100:101] op_sel_hi:[1,0]
	v_rcp_f32_e32 v222, v222
	v_rcp_f32_e32 v223, v223
	v_rcp_f32_e32 v224, v224
	v_rcp_f32_e32 v225, v225
	v_rcp_f32_e32 v226, v226
	v_rcp_f32_e32 v227, v227
	v_rcp_f32_e32 v228, v228
	v_rcp_f32_e32 v229, v229
	v_pk_mul_f32 v[46:47], v[46:47], v[222:223]
	v_pk_mul_f32 v[48:49], v[48:49], v[224:225]
	v_pk_mul_f32 v[42:43], v[42:43], v[226:227]
	v_pk_mul_f32 v[44:45], v[44:45], v[228:229]
	v_lshlrev_b32_e32 v222, 16, v82
	v_and_b32_e32 v223, 0xffff0000, v82
	v_lshlrev_b32_e32 v224, 16, v83
	v_and_b32_e32 v225, 0xffff0000, v83
	v_lshlrev_b32_e32 v226, 16, v84
	v_and_b32_e32 v227, 0xffff0000, v84
	v_lshlrev_b32_e32 v228, 16, v85
	v_and_b32_e32 v229, 0xffff0000, v85
	v_pk_add_f32 v[46:47], v[46:47], v[222:223]
	v_pk_add_f32 v[48:49], v[48:49], v[224:225]
	v_pk_add_f32 v[42:43], v[42:43], v[226:227]
	v_pk_add_f32 v[44:45], v[44:45], v[228:229]
	v_cvt_pk_bf16_f32 v232, v46, v47
	v_cvt_pk_bf16_f32 v233, v48, v49
	v_cvt_pk_bf16_f32 v234, v42, v43
	v_cvt_pk_bf16_f32 v235, v44, v45
	v_lshlrev_b32_e32 v222, 16, v190
	v_and_b32_e32 v223, 0xffff0000, v190
	v_lshlrev_b32_e32 v224, 16, v191
	v_and_b32_e32 v225, 0xffff0000, v191
	v_lshlrev_b32_e32 v226, 16, v192
	v_and_b32_e32 v227, 0xffff0000, v192
	v_lshlrev_b32_e32 v228, 16, v193
	v_and_b32_e32 v229, 0xffff0000, v193
	v_pk_add_f32 v[222:223], v[170:171], v[222:223]
	v_pk_add_f32 v[224:225], v[172:173], v[224:225]
	v_pk_add_f32 v[226:227], v[218:219], v[226:227]
	v_pk_add_f32 v[228:229], v[220:221], v[228:229]
	v_pk_mul_f32 v[222:223], v[222:223], s[98:99] op_sel_hi:[1,0]
	v_pk_mul_f32 v[224:225], v[224:225], s[98:99] op_sel_hi:[1,0]
	v_pk_mul_f32 v[226:227], v[226:227], s[98:99] op_sel_hi:[1,0]
	v_pk_mul_f32 v[228:229], v[228:229], s[98:99] op_sel_hi:[1,0]
	v_exp_f32_e32 v222, v222
	v_exp_f32_e32 v223, v223
	v_exp_f32_e32 v224, v224
	v_exp_f32_e32 v225, v225
	v_exp_f32_e32 v226, v226
	v_exp_f32_e32 v227, v227
	v_exp_f32_e32 v228, v228
	v_exp_f32_e32 v229, v229
	v_pk_add_f32 v[222:223], v[222:223], s[100:101] op_sel_hi:[1,0]
	v_pk_add_f32 v[224:225], v[224:225], s[100:101] op_sel_hi:[1,0]
	v_pk_add_f32 v[226:227], v[226:227], s[100:101] op_sel_hi:[1,0]
	v_pk_add_f32 v[228:229], v[228:229], s[100:101] op_sel_hi:[1,0]
	v_rcp_f32_e32 v222, v222
	v_rcp_f32_e32 v223, v223
	v_rcp_f32_e32 v224, v224
	v_rcp_f32_e32 v225, v225
	v_rcp_f32_e32 v226, v226
	v_rcp_f32_e32 v227, v227
	v_rcp_f32_e32 v228, v228
	v_rcp_f32_e32 v229, v229
	v_pk_mul_f32 v[38:39], v[38:39], v[222:223]
	v_pk_mul_f32 v[40:41], v[40:41], v[224:225]
	v_pk_mul_f32 v[34:35], v[34:35], v[226:227]
	v_pk_mul_f32 v[36:37], v[36:37], v[228:229]
	v_lshlrev_b32_e32 v222, 16, v86
	v_and_b32_e32 v223, 0xffff0000, v86
	v_lshlrev_b32_e32 v224, 16, v87
	v_and_b32_e32 v225, 0xffff0000, v87
	v_lshlrev_b32_e32 v226, 16, v88
	v_and_b32_e32 v227, 0xffff0000, v88
	v_lshlrev_b32_e32 v228, 16, v89
	v_and_b32_e32 v229, 0xffff0000, v89
	v_pk_add_f32 v[38:39], v[38:39], v[222:223]
	v_pk_add_f32 v[40:41], v[40:41], v[224:225]
	v_pk_add_f32 v[34:35], v[34:35], v[226:227]
	v_pk_add_f32 v[36:37], v[36:37], v[228:229]
	v_cvt_pk_bf16_f32 v236, v38, v39
	v_cvt_pk_bf16_f32 v237, v40, v41
	v_cvt_pk_bf16_f32 v238, v34, v35
	v_cvt_pk_bf16_f32 v239, v36, v37
	v_add_u32_e32 v195, 0x48000, v184
	global_store_dwordx4 v195, v[232:235], s[52:53]
	global_store_dwordx4 v195, v[236:239], s[52:53] offset:256
	s_waitcnt vmcnt(12)
; DI unsigned pk2(float lo, float hi) { unsigned r; asm("v_cvt_pk_bf16_f32 %0, %1, %2" : "=v"(r) : "v"(lo), "v"(hi)); return r; }
; DI float bflo(unsigned u) { return __uint_as_float(u << 16); }
; DI float bfhi(unsigned u) { return __uint_as_float(u & 0xffff0000u); }
; DI float fsigmoid(float x) { return frcp(1.0f + fexp2(-1.44269504f * x)); }
;     DI void operator()(const f32x4 (&acc)[2][2][4][2], const Unit& u, int wr, int wc, int fr, int fq) const {
;     ...
;                     for (int bj = 0; bj < 2; ++bj) { const int row = rowb + ai * HALF + (2 * mp + mm) * 16, col = col0 + bj * HALF;
;                         zg[mm][bj] = *(const u32x4*)(Zg + (size_t)row * INW + col);
;                         if (SECOND) yv[mm][bj] = *(const u32x4*)(Y1 + (size_t)row * D + col); }
;                 asm volatile("" ::: "memory");
; #pragma unroll
;                 for (int mm = 0; mm < 2; ++mm)
; #pragma unroll
;                     for (int bj = 0; bj < 2; ++bj) { const int m = 2 * mp + mm; const int row = rowb + ai * HALF + m * 16, col = col0 + bj * HALF;
;                         const u32x4 z = zg[mm][bj]; const f32x4 b0 = bb[bj][0], b1 = bb[bj][1];
;                         f32x4 g0, g1;
;                         g0[0] = fsigmoid(bflo(z.x) + b0[0]); g0[1] = fsigmoid(bfhi(z.x) + b0[1]); g0[2] = fsigmoid(bflo(z.y) + b0[2]); g0[3] = fsigmoid(bfhi(z.y) + b0[3]);
;                         g1[0] = fsigmoid(bflo(z.z) + b1[0]); g1[1] = fsigmoid(bfhi(z.z) + b1[1]); g1[2] = fsigmoid(bflo(z.w) + b1[2]); g1[3] = fsigmoid(bfhi(z.w) + b1[3]);
;                         f32x4 v0 = g0 * acc[ai][bj][m][0], v1 = g1 * acc[ai][bj][m][1];
;                         if (SECOND) { const u32x4 y = yv[mm][bj];
;                             v0[0] += bflo(y.x); v0[1] += bfhi(y.x); v0[2] += bflo(y.y); v0[3] += bfhi(y.y); v1[0] += bflo(y.z); v1[1] += bfhi(y.z); v1[2] += bflo(y.w); v1[3] += bfhi(y.w); }
;                         u32x4 w; w.x = pk2(v0[0], v0[1]); w.y = pk2(v0[2], v0[3]); w.z = pk2(v1[0], v1[1]); w.w = pk2(v1[2], v1[3]);
;                         *(u32x4*)((SECOND ? Mb : Y1) + (size_t)row * D + col) = w; }
	v_lshlrev_b32_e32 v222, 16, v200
	v_and_b32_e32 v223, 0xffff0000, v200
	v_lshlrev_b32_e32 v224, 16, v201
	v_and_b32_e32 v225, 0xffff0000, v201
	v_lshlrev_b32_e32 v226, 16, v202
	v_and_b32_e32 v227, 0xffff0000, v202
	v_lshlrev_b32_e32 v228, 16, v203
	v_and_b32_e32 v229, 0xffff0000, v203
	v_pk_add_f32 v[222:223], v[162:163], v[222:223]
	v_pk_add_f32 v[224:225], v[164:165], v[224:225]
	v_pk_add_f32 v[226:227], v[166:167], v[226:227]
	v_pk_add_f32 v[228:229], v[168:169], v[228:229]
	v_pk_mul_f32 v[222:223], v[222:223], s[98:99] op_sel_hi:[1,0]
	v_pk_mul_f32 v[224:225], v[224:225], s[98:99] op_sel_hi:[1,0]
	v_pk_mul_f32 v[226:227], v[226:227], s[98:99] op_sel_hi:[1,0]
	v_pk_mul_f32 v[228:229], v[228:229], s[98:99] op_sel_hi:[1,0]
	v_exp_f32_e32 v222, v222
	v_exp_f32_e32 v223, v223
	v_exp_f32_e32 v224, v224
	v_exp_f32_e32 v225, v225
	v_exp_f32_e32 v226, v226
	v_exp_f32_e32 v227, v227
	v_exp_f32_e32 v228, v228
	v_exp_f32_e32 v229, v229
	v_pk_add_f32 v[222:223], v[222:223], s[100:101] op_sel_hi:[1,0]
	v_pk_add_f32 v[224:225], v[224:225], s[100:101] op_sel_hi:[1,0]
	v_pk_add_f32 v[226:227], v[226:227], s[100:101] op_sel_hi:[1,0]
	v_pk_add_f32 v[228:229], v[228:229], s[100:101] op_sel_hi:[1,0]
	v_rcp_f32_e32 v222, v222
	v_rcp_f32_e32 v223, v223
	v_rcp_f32_e32 v224, v224
	v_rcp_f32_e32 v225, v225
	v_rcp_f32_e32 v226, v226
	v_rcp_f32_e32 v227, v227
	v_rcp_f32_e32 v228, v228
	v_rcp_f32_e32 v229, v229
	v_pk_mul_f32 v[30:31], v[30:31], v[222:223]
	v_pk_mul_f32 v[32:33], v[32:33], v[224:225]
	v_pk_mul_f32 v[26:27], v[26:27], v[226:227]
	v_pk_mul_f32 v[28:29], v[28:29], v[228:229]
	v_lshlrev_b32_e32 v222, 16, v146
	v_and_b32_e32 v223, 0xffff0000, v146
	v_lshlrev_b32_e32 v224, 16, v147
	v_and_b32_e32 v225, 0xffff0000, v147
	v_lshlrev_b32_e32 v226, 16, v148
	v_and_b32_e32 v227, 0xffff0000, v148
	v_lshlrev_b32_e32 v228, 16, v149
	v_and_b32_e32 v229, 0xffff0000, v149
	v_pk_add_f32 v[30:31], v[30:31], v[222:223]
	v_pk_add_f32 v[32:33], v[32:33], v[224:225]
	v_pk_add_f32 v[26:27], v[26:27], v[226:227]
	v_pk_add_f32 v[28:29], v[28:29], v[228:229]
	v_cvt_pk_bf16_f32 v232, v30, v31
	v_cvt_pk_bf16_f32 v233, v32, v33
	v_cvt_pk_bf16_f32 v234, v26, v27
	v_cvt_pk_bf16_f32 v235, v28, v29
	v_lshlrev_b32_e32 v222, 16, v206
	v_and_b32_e32 v223, 0xffff0000, v206
	v_lshlrev_b32_e32 v224, 16, v207
	v_and_b32_e32 v225, 0xffff0000, v207
	v_lshlrev_b32_e32 v226, 16, v208
	v_and_b32_e32 v227, 0xffff0000, v208
	v_lshlrev_b32_e32 v228, 16, v209
	v_and_b32_e32 v229, 0xffff0000, v209
	v_pk_add_f32 v[222:223], v[170:171], v[222:223]
	v_pk_add_f32 v[224:225], v[172:173], v[224:225]
	v_pk_add_f32 v[226:227], v[218:219], v[226:227]
	v_pk_add_f32 v[228:229], v[220:221], v[228:229]
	v_pk_mul_f32 v[222:223], v[222:223], s[98:99] op_sel_hi:[1,0]
	v_pk_mul_f32 v[224:225], v[224:225], s[98:99] op_sel_hi:[1,0]
	v_pk_mul_f32 v[226:227], v[226:227], s[98:99] op_sel_hi:[1,0]
	v_pk_mul_f32 v[228:229], v[228:229], s[98:99] op_sel_hi:[1,0]
	v_exp_f32_e32 v222, v222
	v_exp_f32_e32 v223, v223
	v_exp_f32_e32 v224, v224
	v_exp_f32_e32 v225, v225
	v_exp_f32_e32 v226, v226
	v_exp_f32_e32 v227, v227
	v_exp_f32_e32 v228, v228
	v_exp_f32_e32 v229, v229
	v_pk_add_f32 v[222:223], v[222:223], s[100:101] op_sel_hi:[1,0]
	v_pk_add_f32 v[224:225], v[224:225], s[100:101] op_sel_hi:[1,0]
	v_pk_add_f32 v[226:227], v[226:227], s[100:101] op_sel_hi:[1,0]
	v_pk_add_f32 v[228:229], v[228:229], s[100:101] op_sel_hi:[1,0]
	v_rcp_f32_e32 v222, v222
	v_rcp_f32_e32 v223, v223
	v_rcp_f32_e32 v224, v224
	v_rcp_f32_e32 v225, v225
	v_rcp_f32_e32 v226, v226
	v_rcp_f32_e32 v227, v227
	v_rcp_f32_e32 v228, v228
	v_rcp_f32_e32 v229, v229
	v_pk_mul_f32 v[22:23], v[22:23], v[222:223]
	v_pk_mul_f32 v[24:25], v[24:25], v[224:225]
	v_pk_mul_f32 v[18:19], v[18:19], v[226:227]
	v_pk_mul_f32 v[20:21], v[20:21], v[228:229]
	v_lshlrev_b32_e32 v222, 16, v150
	v_and_b32_e32 v223, 0xffff0000, v150
	v_lshlrev_b32_e32 v224, 16, v151
	v_and_b32_e32 v225, 0xffff0000, v151
	v_lshlrev_b32_e32 v226, 16, v152
	v_and_b32_e32 v227, 0xffff0000, v152
	v_lshlrev_b32_e32 v228, 16, v153
	v_and_b32_e32 v229, 0xffff0000, v153
	v_pk_add_f32 v[22:23], v[22:23], v[222:223]
	v_pk_add_f32 v[24:25], v[24:25], v[224:225]
	v_pk_add_f32 v[18:19], v[18:19], v[226:227]
	v_pk_add_f32 v[20:21], v[20:21], v[228:229]
	v_cvt_pk_bf16_f32 v236, v22, v23
	v_cvt_pk_bf16_f32 v237, v24, v25
	v_cvt_pk_bf16_f32 v238, v18, v19
	v_cvt_pk_bf16_f32 v239, v20, v21
	v_add_u32_e32 v195, 0x50000, v184
	global_store_dwordx4 v195, v[232:235], s[52:53]
	global_store_dwordx4 v195, v[236:239], s[52:53] offset:256
	s_waitcnt vmcnt(8)
; DI unsigned pk2(float lo, float hi) { unsigned r; asm("v_cvt_pk_bf16_f32 %0, %1, %2" : "=v"(r) : "v"(lo), "v"(hi)); return r; }
; DI float bflo(unsigned u) { return __uint_as_float(u << 16); }
; DI float bfhi(unsigned u) { return __uint_as_float(u & 0xffff0000u); }
; DI float fsigmoid(float x) { return frcp(1.0f + fexp2(-1.44269504f * x)); }
;     DI void operator()(const f32x4 (&acc)[2][2][4][2], const Unit& u, int wr, int wc, int fr, int fq) const {
;     ...
;                     for (int bj = 0; bj < 2; ++bj) { const int row = rowb + ai * HALF + (2 * mp + mm) * 16, col = col0 + bj * HALF;
;                         zg[mm][bj] = *(const u32x4*)(Zg + (size_t)row * INW + col);
;                         if (SECOND) yv[mm][bj] = *(const u32x4*)(Y1 + (size_t)row * D + col); }
;                 asm volatile("" ::: "memory");
; #pragma unroll
;                 for (int mm = 0; mm < 2; ++mm)
; #pragma unroll
;                     for (int bj = 0; bj < 2; ++bj) { const int m = 2 * mp + mm; const int row = rowb + ai * HALF + m * 16, col = col0 + bj * HALF;
;                         const u32x4 z = zg[mm][bj]; const f32x4 b0 = bb[bj][0], b1 = bb[bj][1];
;                         f32x4 g0, g1;
;                         g0[0] = fsigmoid(bflo(z.x) + b0[0]); g0[1] = fsigmoid(bfhi(z.x) + b0[1]); g0[2] = fsigmoid(bflo(z.y) + b0[2]); g0[3] = fsigmoid(bfhi(z.y) + b0[3]);
;                         g1[0] = fsigmoid(bflo(z.z) + b1[0]); g1[1] = fsigmoid(bfhi(z.z) + b1[1]); g1[2] = fsigmoid(bflo(z.w) + b1[2]); g1[3] = fsigmoid(bfhi(z.w) + b1[3]);
;                         f32x4 v0 = g0 * acc[ai][bj][m][0], v1 = g1 * acc[ai][bj][m][1];
;                         if (SECOND) { const u32x4 y = yv[mm][bj];
;                             v0[0] += bflo(y.x); v0[1] += bfhi(y.x); v0[2] += bflo(y.y); v0[3] += bfhi(y.y); v1[0] += bflo(y.z); v1[1] += bfhi(y.z); v1[2] += bflo(y.w); v1[3] += bfhi(y.w); }
;                         u32x4 w; w.x = pk2(v0[0], v0[1]); w.y = pk2(v0[2], v0[3]); w.z = pk2(v1[0], v1[1]); w.w = pk2(v1[2], v1[3]);
;                         *(u32x4*)((SECOND ? Mb : Y1) + (size_t)row * D + col) = w; }
	v_lshlrev_b32_e32 v222, 16, v210
	v_and_b32_e32 v223, 0xffff0000, v210
	v_lshlrev_b32_e32 v224, 16, v211
	v_and_b32_e32 v225, 0xffff0000, v211
	v_lshlrev_b32_e32 v226, 16, v212
	v_and_b32_e32 v227, 0xffff0000, v212
	v_lshlrev_b32_e32 v228, 16, v213
	v_and_b32_e32 v229, 0xffff0000, v213
	v_pk_add_f32 v[222:223], v[162:163], v[222:223]
	v_pk_add_f32 v[224:225], v[164:165], v[224:225]
	v_pk_add_f32 v[226:227], v[166:167], v[226:227]
	v_pk_add_f32 v[228:229], v[168:169], v[228:229]
	v_pk_mul_f32 v[222:223], v[222:223], s[98:99] op_sel_hi:[1,0]
	v_pk_mul_f32 v[224:225], v[224:225], s[98:99] op_sel_hi:[1,0]
	v_pk_mul_f32 v[226:227], v[226:227], s[98:99] op_sel_hi:[1,0]
	v_pk_mul_f32 v[228:229], v[228:229], s[98:99] op_sel_hi:[1,0]
	v_exp_f32_e32 v222, v222
	v_exp_f32_e32 v223, v223
	v_exp_f32_e32 v224, v224
	v_exp_f32_e32 v225, v225
	v_exp_f32_e32 v226, v226
	v_exp_f32_e32 v227, v227
	v_exp_f32_e32 v228, v228
	v_exp_f32_e32 v229, v229
	v_pk_add_f32 v[222:223], v[222:223], s[100:101] op_sel_hi:[1,0]
	v_pk_add_f32 v[224:225], v[224:225], s[100:101] op_sel_hi:[1,0]
	v_pk_add_f32 v[226:227], v[226:227], s[100:101] op_sel_hi:[1,0]
	v_pk_add_f32 v[228:229], v[228:229], s[100:101] op_sel_hi:[1,0]
	v_rcp_f32_e32 v222, v222
	v_rcp_f32_e32 v223, v223
	v_rcp_f32_e32 v224, v224
	v_rcp_f32_e32 v225, v225
	v_rcp_f32_e32 v226, v226
	v_rcp_f32_e32 v227, v227
	v_rcp_f32_e32 v228, v228
	v_rcp_f32_e32 v229, v229
	v_pk_mul_f32 v[14:15], v[14:15], v[222:223]
	v_pk_mul_f32 v[16:17], v[16:17], v[224:225]
	v_pk_mul_f32 v[10:11], v[10:11], v[226:227]
	v_pk_mul_f32 v[12:13], v[12:13], v[228:229]
	v_lshlrev_b32_e32 v222, 16, v154
	v_and_b32_e32 v223, 0xffff0000, v154
	v_lshlrev_b32_e32 v224, 16, v155
	v_and_b32_e32 v225, 0xffff0000, v155
	v_lshlrev_b32_e32 v226, 16, v156
	v_and_b32_e32 v227, 0xffff0000, v156
	v_lshlrev_b32_e32 v228, 16, v157
	v_and_b32_e32 v229, 0xffff0000, v157
	v_pk_add_f32 v[14:15], v[14:15], v[222:223]
	v_pk_add_f32 v[16:17], v[16:17], v[224:225]
	v_pk_add_f32 v[10:11], v[10:11], v[226:227]
	v_pk_add_f32 v[12:13], v[12:13], v[228:229]
	v_cvt_pk_bf16_f32 v232, v14, v15
	v_cvt_pk_bf16_f32 v233, v16, v17
	v_cvt_pk_bf16_f32 v234, v10, v11
	v_cvt_pk_bf16_f32 v235, v12, v13
	v_lshlrev_b32_e32 v222, 16, v214
	v_and_b32_e32 v223, 0xffff0000, v214
	v_lshlrev_b32_e32 v224, 16, v215
	v_and_b32_e32 v225, 0xffff0000, v215
	v_lshlrev_b32_e32 v226, 16, v216
	v_and_b32_e32 v227, 0xffff0000, v216
	v_lshlrev_b32_e32 v228, 16, v217
	v_and_b32_e32 v229, 0xffff0000, v217
	v_pk_add_f32 v[222:223], v[170:171], v[222:223]
	v_pk_add_f32 v[224:225], v[172:173], v[224:225]
	v_pk_add_f32 v[226:227], v[218:219], v[226:227]
	v_pk_add_f32 v[228:229], v[220:221], v[228:229]
	v_pk_mul_f32 v[222:223], v[222:223], s[98:99] op_sel_hi:[1,0]
	v_pk_mul_f32 v[224:225], v[224:225], s[98:99] op_sel_hi:[1,0]
	v_pk_mul_f32 v[226:227], v[226:227], s[98:99] op_sel_hi:[1,0]
	v_pk_mul_f32 v[228:229], v[228:229], s[98:99] op_sel_hi:[1,0]
	v_exp_f32_e32 v222, v222
	v_exp_f32_e32 v223, v223
	v_exp_f32_e32 v224, v224
	v_exp_f32_e32 v225, v225
	v_exp_f32_e32 v226, v226
	v_exp_f32_e32 v227, v227
	v_exp_f32_e32 v228, v228
	v_exp_f32_e32 v229, v229
	v_pk_add_f32 v[222:223], v[222:223], s[100:101] op_sel_hi:[1,0]
	v_pk_add_f32 v[224:225], v[224:225], s[100:101] op_sel_hi:[1,0]
	v_pk_add_f32 v[226:227], v[226:227], s[100:101] op_sel_hi:[1,0]
	v_pk_add_f32 v[228:229], v[228:229], s[100:101] op_sel_hi:[1,0]
	v_rcp_f32_e32 v222, v222
	v_rcp_f32_e32 v223, v223
	v_rcp_f32_e32 v224, v224
	v_rcp_f32_e32 v225, v225
	v_rcp_f32_e32 v226, v226
	v_rcp_f32_e32 v227, v227
	v_rcp_f32_e32 v228, v228
	v_rcp_f32_e32 v229, v229
	v_pk_mul_f32 v[6:7], v[6:7], v[222:223]
	v_pk_mul_f32 v[8:9], v[8:9], v[224:225]
	v_pk_mul_f32 v[2:3], v[2:3], v[226:227]
	v_pk_mul_f32 v[4:5], v[4:5], v[228:229]
	v_lshlrev_b32_e32 v222, 16, v158
	v_and_b32_e32 v223, 0xffff0000, v158
	v_lshlrev_b32_e32 v224, 16, v159
	v_and_b32_e32 v225, 0xffff0000, v159
	v_lshlrev_b32_e32 v226, 16, v160
	v_and_b32_e32 v227, 0xffff0000, v160
	v_lshlrev_b32_e32 v228, 16, v161
	v_and_b32_e32 v229, 0xffff0000, v161
	v_pk_add_f32 v[6:7], v[6:7], v[222:223]
	v_pk_add_f32 v[8:9], v[8:9], v[224:225]
	v_pk_add_f32 v[2:3], v[2:3], v[226:227]
	v_pk_add_f32 v[4:5], v[4:5], v[228:229]
	v_cvt_pk_bf16_f32 v236, v6, v7
	v_cvt_pk_bf16_f32 v237, v8, v9
	v_cvt_pk_bf16_f32 v238, v2, v3
	v_cvt_pk_bf16_f32 v239, v4, v5
	v_add_u32_e32 v195, 0x58000, v184
	global_store_dwordx4 v195, v[232:235], s[52:53]
	global_store_dwordx4 v195, v[236:239], s[52:53] offset:256
	s_andn2_b64 vcc, exec, s[4:5]
	s_mov_b64 s[4:5], -1
	s_cbranch_vccnz .LBB0_531
	s_andn2_b64 vcc, exec, s[6:7]
	s_cbranch_vccnz .LBB0_530
	s_barrier
	s_branch .LBB0_530
